# prenorm XN (bf16 row) stores non-temporal, to shorten the L2 writeback at the phase-2 barrier
# speedup vs baseline: 1.0040x; 1.0040x over previous
; __device__ __forceinline__ unsigned cvt_pk_bf16(float lo, float hi) { unsigned r; asm volatile("v_cvt_pk_bf16_f32 %0, %1, %2" : "=v"(r) : "v"(lo), "v"(hi)); return r; }
; __device__ __forceinline__ void prenorm_rows(const float* src0, const float* src1, int row_lo, int row_hi, const float* g, const float* scale, float* SS, bf16_t* HB) {
;     ...
;         const f32x4* gp = (const f32x4*)g + lane;
;         const f32x4* sca = (const f32x4*)(scale + (size_t)mba * 9216) + lane; const f32x4* scb = (const f32x4*)(scale + (size_t)mbb * 9216) + lane;
;         u32x2* oa = (u32x2*)(HB + (size_t)row * D) + lane; u32x2* ob = (u32x2*)(HB + (size_t)rb * D) + lane;
; #pragma unroll
;         for (int j = 0; j < 4; ++j) { const f32x4 gj = gp[64 * j]; const f32x4 za = va[j] * gj * (sca[64 * j] + 1.0f), zb = vb[j] * gj * (scb[64 * j] + 1.0f);
;             u32x2 w; w.x = cvt_pk_bf16(za[0], za[1]); w.y = cvt_pk_bf16(za[2], za[3]); oa[64 * j] = w;
;             if (hasb) { w.x = cvt_pk_bf16(zb[0], zb[1]); w.y = cvt_pk_bf16(zb[2], zb[3]); ob[64 * j] = w; } }
.LBB0_140:
	s_or_b64 exec, exec, s[12:13]
	v_min_i32_e32 v32, 0x4000, v48
	v_ashrrev_i32_e32 v32, 12, v32
	v_mul_hi_i32_i24_e32 v37, 0x9000, v32
	v_mul_i32_i24_e32 v36, 0x9000, v32
	v_lshl_add_u64 v[52:53], v[42:43], 0, v[36:37]
	v_min_i32_e32 v36, 0x4000, v50
	v_ashrrev_i32_e32 v36, 12, v36
	s_waitcnt lgkmcnt(0)
	global_load_dwordx4 v[32:35], v[40:41], off
	global_load_dwordx4 v[68:71], v[52:53], off
	v_mul_hi_i32_i24_e32 v37, 0x9000, v36
	v_mul_i32_i24_e32 v36, 0x9000, v36
	v_lshl_add_u64 v[54:55], v[42:43], 0, v[36:37]
	global_load_dwordx4 v[36:39], v[54:55], off
	v_lshlrev_b64 v[48:49], 11, v[48:49]
	v_lshlrev_b64 v[72:73], 11, v[50:51]
	v_lshl_add_u64 v[50:51], v[44:45], 0, v[48:49]
	v_lshl_add_u64 v[48:49], v[44:45], 0, v[72:73]
	s_waitcnt vmcnt(2)
	v_pk_mul_f32 v[28:29], v[28:29], v[32:33]
	s_waitcnt vmcnt(1)
	v_pk_add_f32 v[68:69], v[68:69], 1.0 op_sel_hi:[1,0]
	v_pk_mul_f32 v[30:31], v[30:31], v[34:35]
	v_pk_add_f32 v[70:71], v[70:71], 1.0 op_sel_hi:[1,0]
	v_pk_mul_f32 v[28:29], v[28:29], v[68:69]
	v_pk_mul_f32 v[30:31], v[30:31], v[70:71]
	v_cvt_pk_bf16_f32 v28, v28, v29
	s_nop 0
	v_cvt_pk_bf16_f32 v29, v30, v31
	global_store_dwordx2 v[50:51], v[28:29], off nt
	s_and_saveexec_b64 s[12:13], s[0:1]
	s_cbranch_execz .LBB0_142
	v_pk_mul_f32 v[24:25], v[24:25], v[32:33]
	s_waitcnt vmcnt(1)
	v_pk_add_f32 v[30:31], v[36:37], 1.0 op_sel_hi:[1,0]
	v_pk_mul_f32 v[26:27], v[26:27], v[34:35]
	v_pk_add_f32 v[28:29], v[38:39], 1.0 op_sel_hi:[1,0]
	v_pk_mul_f32 v[24:25], v[24:25], v[30:31]
	v_pk_mul_f32 v[26:27], v[26:27], v[28:29]
	v_cvt_pk_bf16_f32 v24, v24, v25
	s_nop 0
	v_cvt_pk_bf16_f32 v25, v26, v27
	global_store_dwordx2 v[48:49], v[24:25], off nt
.LBB0_142:
	s_or_b64 exec, exec, s[12:13]
	global_load_dwordx4 v[24:27], v[40:41], off offset:1024
	global_load_dwordx4 v[32:35], v[52:53], off offset:1024
	global_load_dwordx4 v[28:31], v[54:55], off offset:1024
	s_waitcnt vmcnt(2)
	v_pk_mul_f32 v[20:21], v[20:21], v[24:25]
	s_waitcnt vmcnt(1)
	v_pk_add_f32 v[32:33], v[32:33], 1.0 op_sel_hi:[1,0]
	v_pk_mul_f32 v[22:23], v[22:23], v[26:27]
	v_pk_add_f32 v[34:35], v[34:35], 1.0 op_sel_hi:[1,0]
	v_pk_mul_f32 v[20:21], v[20:21], v[32:33]
	v_pk_mul_f32 v[22:23], v[22:23], v[34:35]
	v_cvt_pk_bf16_f32 v20, v20, v21
	s_nop 0
	v_cvt_pk_bf16_f32 v21, v22, v23
	global_store_dwordx2 v[50:51], v[20:21], off offset:512 nt
	s_and_saveexec_b64 s[12:13], s[0:1]
	s_cbranch_execz .LBB0_144
	v_pk_mul_f32 v[16:17], v[16:17], v[24:25]
	s_waitcnt vmcnt(1)
	v_pk_add_f32 v[22:23], v[28:29], 1.0 op_sel_hi:[1,0]
	v_pk_mul_f32 v[18:19], v[18:19], v[26:27]
	v_pk_add_f32 v[20:21], v[30:31], 1.0 op_sel_hi:[1,0]
	v_pk_mul_f32 v[16:17], v[16:17], v[22:23]
	v_pk_mul_f32 v[18:19], v[18:19], v[20:21]
	v_cvt_pk_bf16_f32 v16, v16, v17
	s_nop 0
	v_cvt_pk_bf16_f32 v17, v18, v19
	global_store_dwordx2 v[48:49], v[16:17], off offset:512 nt
.LBB0_144:
	s_or_b64 exec, exec, s[12:13]
	global_load_dwordx4 v[16:19], v[40:41], off offset:2048
	global_load_dwordx4 v[24:27], v[52:53], off offset:2048
	global_load_dwordx4 v[20:23], v[54:55], off offset:2048
	s_waitcnt vmcnt(2)
	v_pk_mul_f32 v[12:13], v[12:13], v[16:17]
	s_waitcnt vmcnt(1)
	v_pk_add_f32 v[24:25], v[24:25], 1.0 op_sel_hi:[1,0]
	v_pk_mul_f32 v[14:15], v[14:15], v[18:19]
	v_pk_add_f32 v[26:27], v[26:27], 1.0 op_sel_hi:[1,0]
	v_pk_mul_f32 v[12:13], v[12:13], v[24:25]
	v_pk_mul_f32 v[14:15], v[14:15], v[26:27]
	v_cvt_pk_bf16_f32 v12, v12, v13
	s_nop 0
	v_cvt_pk_bf16_f32 v13, v14, v15
	global_store_dwordx2 v[50:51], v[12:13], off offset:1024 nt
	s_and_saveexec_b64 s[12:13], s[0:1]
	s_cbranch_execz .LBB0_146
	v_pk_mul_f32 v[8:9], v[8:9], v[16:17]
	s_waitcnt vmcnt(1)
	v_pk_add_f32 v[14:15], v[20:21], 1.0 op_sel_hi:[1,0]
	v_pk_mul_f32 v[10:11], v[10:11], v[18:19]
	v_pk_add_f32 v[12:13], v[22:23], 1.0 op_sel_hi:[1,0]
	v_pk_mul_f32 v[8:9], v[8:9], v[14:15]
	v_pk_mul_f32 v[10:11], v[10:11], v[12:13]
	v_cvt_pk_bf16_f32 v8, v8, v9
	s_nop 0
	v_cvt_pk_bf16_f32 v9, v10, v11
	global_store_dwordx2 v[48:49], v[8:9], off offset:1024 nt
.LBB0_146:
	s_or_b64 exec, exec, s[12:13]
	global_load_dwordx4 v[8:11], v[40:41], off offset:3072
	global_load_dwordx4 v[16:19], v[52:53], off offset:3072
	global_load_dwordx4 v[12:15], v[54:55], off offset:3072
	s_waitcnt vmcnt(2)
	v_pk_mul_f32 v[4:5], v[4:5], v[8:9]
	s_waitcnt vmcnt(1)
	v_pk_add_f32 v[16:17], v[16:17], 1.0 op_sel_hi:[1,0]
	v_pk_mul_f32 v[6:7], v[6:7], v[10:11]
	v_pk_add_f32 v[18:19], v[18:19], 1.0 op_sel_hi:[1,0]
	v_pk_mul_f32 v[4:5], v[4:5], v[16:17]
	v_pk_mul_f32 v[6:7], v[6:7], v[18:19]
	v_cvt_pk_bf16_f32 v4, v4, v5
	s_nop 0
	v_cvt_pk_bf16_f32 v5, v6, v7
	global_store_dwordx2 v[50:51], v[4:5], off offset:1536 nt
	s_and_saveexec_b64 s[12:13], s[0:1]
	s_cbranch_execz .LBB0_136
	v_pk_mul_f32 v[0:1], v[0:1], v[8:9]
	s_waitcnt vmcnt(1)
	v_pk_add_f32 v[6:7], v[12:13], 1.0 op_sel_hi:[1,0]
	v_pk_mul_f32 v[2:3], v[2:3], v[10:11]
	v_pk_add_f32 v[4:5], v[14:15], 1.0 op_sel_hi:[1,0]
	v_pk_mul_f32 v[0:1], v[0:1], v[6:7]
	v_pk_mul_f32 v[2:3], v[2:3], v[4:5]
	v_cvt_pk_bf16_f32 v0, v0, v1
	s_nop 0
	v_cvt_pk_bf16_f32 v1, v2, v3
	global_store_dwordx2 v[48:49], v[0:1], off offset:1536 nt
	s_branch .LBB0_136
